# attention mix0: K-tile load addresses strength-reduced to per-lane incremental pointers
# baseline (speedup 1.0000x reference)
.LBB0_602:
	v_bfe_u32 v0, v24, 2, 2
	v_lshl_or_b32 v0, v25, 2, v0
	v_mad_u32_u24 v4, v0, s43, 0
	v_and_b32_e32 v0, 16, v24
	v_lshlrev_b32_e32 v1, 2, v24
	s_and_b64 s[6:7], s[6:7], exec
	v_and_or_b32 v0, v1, 12, v0
	v_lshlrev_b64 v[2:3], 12, v[174:175]
	s_cselect_b32 s13, 4, 0x44
	v_lshlrev_b32_e32 v5, 1, v0
	v_subrev_u32_e32 v0, 64, v36
	v_mov_b32_e32 v1, v129
	v_lshl_add_u64 v[2:3], s[92:93], 0, v[2:3]
	s_add_u32 s0, s1, s0
	v_mov_b32_e32 v31, v129
	v_lshl_add_u64 v[178:179], v[0:1], 1, v[2:3]
	v_lshl_add_u64 v[0:1], s[92:93], 0, v[28:29]
	s_addc_u32 s1, 0, 0
	v_ashrrev_i32_e32 v37, 31, v36
	v_lshl_add_u64 v[180:181], v[30:31], 1, v[0:1]
	v_lshl_add_u64 v[0:1], s[0:1], 0, v[38:39]
	v_lshl_add_u64 v[130:131], v[26:27], 1, s[8:9]
	v_cmp_gt_i32_e64 s[6:7], 8, v34
	s_mov_b32 s33, 3
	v_lshl_add_u64 v[176:177], v[36:37], 1, s[8:9]
	v_add_u32_e32 v204, 0, v33
	v_lshl_add_u64 v[182:183], v[0:1], 0, v[128:129]
	v_add_u32_e32 v175, v4, v5
	v_mov_b32_e32 v33, v32
	v_mov_b32_e32 v34, v32
	v_mov_b32_e32 v35, v32
	v_mov_b32_e32 v36, v32
	v_mov_b32_e32 v37, v32
	v_mov_b32_e32 v38, v32
	v_mov_b32_e32 v39, v32
	v_mov_b32_e32 v40, v32
	v_mov_b32_e32 v41, v32
	v_mov_b32_e32 v42, v32
	v_mov_b32_e32 v43, v32
	v_mov_b32_e32 v44, v32
	v_mov_b32_e32 v45, v32
	v_mov_b32_e32 v46, v32
	v_mov_b32_e32 v47, v32
	v_mov_b32_e32 v16, v205
	v_mov_b32_e32 v17, v205
	v_mov_b32_e32 v18, v205
	v_mov_b32_e32 v19, v205
	v_mov_b32_e32 v20, v205
	v_mov_b32_e32 v21, v205
	v_mov_b32_e32 v22, v205
	v_mov_b32_e32 v23, v205
	v_mov_b32_e32 v24, v205
	v_mov_b32_e32 v25, v205
	v_mov_b32_e32 v26, v205
	v_mov_b32_e32 v27, v205
	v_mov_b32_e32 v28, v205
	v_mov_b32_e32 v29, v205
	v_mov_b32_e32 v30, v205
	v_mov_b32_e32 v31, v205
	v_mov_b32_e32 v0, v205
	v_mov_b32_e32 v1, v205
	v_mov_b32_e32 v2, v205
	v_mov_b32_e32 v3, v205
	v_mov_b32_e32 v4, v205
	v_mov_b32_e32 v5, v205
	v_mov_b32_e32 v6, v205
	v_mov_b32_e32 v7, v205
	v_mov_b32_e32 v8, v205
	v_mov_b32_e32 v9, v205
	v_mov_b32_e32 v10, v205
	v_mov_b32_e32 v11, v205
	v_mov_b32_e32 v12, v205
	v_mov_b32_e32 v13, v205
	v_mov_b32_e32 v14, v205
	v_mov_b32_e32 v15, v205
	s_add_i32 s0, s40, 2
	s_lshl_b32 s0, s0, 6
	v_add_u32_e32 v82, s0, v172
	v_mad_i64_i32 v[82:83], s[10:11], v82, s49, v[130:131]
	v_lshl_add_u64 v[82:83], v[82:83], 0, s[96:97]
	v_lshl_add_u64 v[80:81], s[74:75], 0, v[180:181]
	v_lshl_add_u64 v[80:81], v[80:81], 0, s[34:35]
	v_cndmask_b32_e64 v130, v80, v82, s[2:3]
	v_cndmask_b32_e64 v131, v81, v83, s[2:3]
	v_mov_b32_e32 v180, 0x40000
	v_mov_b32_e32 v80, 0x38000
	v_cndmask_b32_e64 v180, v180, v80, s[2:3]
	v_add_u32_e32 v82, s0, v174
	v_mad_i64_i32 v[82:83], s[10:11], v82, s49, v[176:177]
	v_lshl_add_u64 v[82:83], v[82:83], 0, s[96:97]
	v_lshl_add_u64 v[80:81], s[74:75], 0, v[178:179]
	v_lshl_add_u64 v[80:81], v[80:81], 0, s[34:35]
	v_cndmask_b32_e64 v176, v80, v82, s[6:7]
	v_cndmask_b32_e64 v177, v81, v83, s[6:7]
	v_mov_b32_e32 v178, 0x40000
	v_mov_b32_e32 v80, 0x38000
	v_cndmask_b32_e64 v178, v178, v80, s[6:7]
	s_barrier
.LBB0_603:
	s_add_i32 s44, s40, 2
	s_add_i32 s85, s33, -1
	s_cmp_lt_u32 s85, s13
	s_cselect_b64 s[38:39], -1, 0
	s_cmp_ge_u32 s85, s13
	s_cbranch_scc1 .LBB0_615
	global_load_dwordx4 v[132:135], v[130:131], off
	v_add_co_u32_e32 v130, vcc, v180, v130
	s_nop 1
	v_addc_co_u32_e32 v131, vcc, 0, v131, vcc
	s_and_saveexec_b64 s[8:9], s[4:5]
	s_cbranch_execz .Lm0a_s1
	global_load_dwordx4 v[140:143], v[176:177], off
	v_add_co_u32_e32 v176, vcc, v178, v176
	s_nop 1
	v_addc_co_u32_e32 v177, vcc, 0, v177, vcc

.LBB0_625:
	s_cmp_lt_u32 s33, s13
	s_cselect_b64 s[10:11], -1, 0
	s_cmp_ge_u32 s33, s13
	s_waitcnt lgkmcnt(0)
	s_barrier
	s_cbranch_scc1 .LBB0_637
	global_load_dwordx4 v[132:135], v[130:131], off
	v_add_co_u32_e32 v130, vcc, v180, v130
	s_nop 1
	v_addc_co_u32_e32 v131, vcc, 0, v131, vcc
	s_and_saveexec_b64 s[38:39], s[4:5]
	s_cbranch_execz .Lm0a_s2
	global_load_dwordx4 v[140:143], v[176:177], off
	v_add_co_u32_e32 v176, vcc, v178, v176
	s_nop 1
	v_addc_co_u32_e32 v177, vcc, 0, v177, vcc

.LBB0_647:
	s_add_i32 s33, s33, 2
	s_mov_b64 s[0:1], 0x70000
	s_cmp_lt_u32 s85, s13
	v_lshl_add_u64 v[182:183], v[182:183], 0, s[0:1]
	s_waitcnt lgkmcnt(0)
	s_barrier
	s_cbranch_scc0 .LBB0_497
	s_mov_b32 s40, s44
	s_branch .LBB0_603

.LBB0_1837:
	v_bfe_u32 v0, v28, 2, 2
	v_lshl_or_b32 v0, v29, 2, v0
	v_mad_u32_u24 v4, v0, s49, 0
	v_and_b32_e32 v0, 16, v28
	v_lshlrev_b32_e32 v1, 2, v28
	v_mov_b32_e32 v37, v129
	v_lshl_add_u64 v[2:3], s[14:15], 0, v[34:35]
	v_and_or_b32 v0, v1, 12, v0
	s_mul_i32 s42, s42, 0xee0000
	v_lshl_add_u64 v[178:179], v[36:37], 1, v[2:3]
	v_lshlrev_b64 v[2:3], 12, v[174:175]
	v_lshlrev_b32_e32 v5, 1, v0
	v_subrev_u32_e32 v0, 64, v40
	v_mov_b32_e32 v1, v129
	v_lshl_add_u64 v[2:3], s[14:15], 0, v[2:3]
	s_or_b32 s14, s13, s42
	v_ashrrev_i32_e32 v41, 31, v40
	v_lshl_add_u64 v[180:181], v[0:1], 1, v[2:3]
	v_lshl_add_u64 v[0:1], s[14:15], 0, v[90:91]
	v_lshl_add_u64 v[130:131], v[30:31], 1, s[8:9]
	v_cmp_gt_i32_e64 s[6:7], 8, v38
	v_lshl_add_u64 v[176:177], v[40:41], 1, s[8:9]
	v_add_u32_e32 v205, 0, v33
	v_lshl_add_u64 v[182:183], v[0:1], 0, v[128:129]
	v_add_u32_e32 v175, v4, v5
	v_mov_b32_e32 v33, v32
	v_mov_b32_e32 v34, v32
	v_mov_b32_e32 v35, v32
	v_mov_b32_e32 v36, v32
	v_mov_b32_e32 v37, v32
	v_mov_b32_e32 v38, v32
	v_mov_b32_e32 v39, v32
	v_mov_b32_e32 v40, v32
	v_mov_b32_e32 v41, v32
	v_mov_b32_e32 v42, v32
	v_mov_b32_e32 v43, v32
	v_mov_b32_e32 v44, v32
	v_mov_b32_e32 v45, v32
	v_mov_b32_e32 v46, v32
	v_mov_b32_e32 v47, v32
	v_mov_b32_e32 v16, v206
	v_mov_b32_e32 v17, v206
	v_mov_b32_e32 v18, v206
	v_mov_b32_e32 v19, v206
	v_mov_b32_e32 v20, v206
	v_mov_b32_e32 v21, v206
	v_mov_b32_e32 v22, v206
	v_mov_b32_e32 v23, v206
	v_mov_b32_e32 v24, v206
	v_mov_b32_e32 v25, v206
	v_mov_b32_e32 v26, v206
	v_mov_b32_e32 v27, v206
	v_mov_b32_e32 v28, v206
	v_mov_b32_e32 v29, v206
	v_mov_b32_e32 v30, v206
	v_mov_b32_e32 v31, v206
	v_mov_b32_e32 v0, v206
	v_mov_b32_e32 v1, v206
	v_mov_b32_e32 v2, v206
	v_mov_b32_e32 v3, v206
	v_mov_b32_e32 v4, v206
	v_mov_b32_e32 v5, v206
	v_mov_b32_e32 v6, v206
	v_mov_b32_e32 v7, v206
	v_mov_b32_e32 v8, v206
	v_mov_b32_e32 v9, v206
	v_mov_b32_e32 v10, v206
	v_mov_b32_e32 v11, v206
	v_mov_b32_e32 v12, v206
	v_mov_b32_e32 v13, v206
	v_mov_b32_e32 v14, v206
	v_mov_b32_e32 v15, v206
	s_add_i32 s14, s20, 2
	s_lshl_b32 s14, s14, 6
	v_add_u32_e32 v82, s14, v172
	v_mad_i64_i32 v[82:83], s[24:25], v82, s67, v[130:131]
	v_lshl_add_u64 v[82:83], v[82:83], 0, s[18:19]
	v_lshl_add_u64 v[80:81], s[74:75], 0, v[178:179]
	v_lshl_add_u64 v[80:81], v[80:81], 0, s[34:35]
	v_cndmask_b32_e64 v130, v80, v82, s[2:3]
	v_cndmask_b32_e64 v131, v81, v83, s[2:3]
	v_mov_b32_e32 v178, 0x40000
	v_mov_b32_e32 v80, 0x38000
	v_cndmask_b32_e64 v178, v178, v80, s[2:3]
	v_add_u32_e32 v82, s14, v174
	v_mad_i64_i32 v[82:83], s[24:25], v82, s67, v[176:177]
	v_lshl_add_u64 v[82:83], v[82:83], 0, s[18:19]
	v_lshl_add_u64 v[80:81], s[74:75], 0, v[180:181]
	v_lshl_add_u64 v[80:81], v[80:81], 0, s[34:35]
	v_cndmask_b32_e64 v176, v80, v82, s[6:7]
	v_cndmask_b32_e64 v177, v81, v83, s[6:7]
	v_mov_b32_e32 v180, 0x40000
	v_mov_b32_e32 v80, 0x38000
	v_cndmask_b32_e64 v180, v180, v80, s[6:7]
	s_barrier
.LBB0_1838:
	s_add_i32 s13, s20, 2
	s_cmpk_lt_u32 s20, 0x42
	s_cselect_b64 s[40:41], -1, 0
	s_cmpk_gt_u32 s20, 0x41
	s_cselect_b64 s[38:39], -1, 0
	s_and_b64 vcc, exec, s[38:39]
	s_cbranch_vccnz .LBB0_1850
	global_load_dwordx4 v[132:135], v[130:131], off
	v_add_co_u32_e32 v130, vcc, v178, v130
	s_nop 1
	v_addc_co_u32_e32 v131, vcc, 0, v131, vcc
	s_and_saveexec_b64 s[8:9], s[4:5]
	s_cbranch_execz .Lm0b_s1
	global_load_dwordx4 v[136:139], v[176:177], off
	v_add_co_u32_e32 v176, vcc, v180, v176
	s_nop 1
	v_addc_co_u32_e32 v177, vcc, 0, v177, vcc

.LBB0_1855:
	s_cmpk_lt_u32 s20, 0x41
	s_cselect_b64 s[40:41], -1, 0
	s_cmp_gt_u32 s20, 64
	s_waitcnt vmcnt(0)
	ds_write_b128 v202, v[164:167] offset:38912
	s_waitcnt lgkmcnt(0)
	s_barrier
	s_cbranch_scc1 .LBB0_1867
	global_load_dwordx4 v[132:135], v[130:131], off
	v_add_co_u32_e32 v130, vcc, v178, v130
	s_nop 1
	v_addc_co_u32_e32 v131, vcc, 0, v131, vcc
	s_and_saveexec_b64 s[42:43], s[4:5]
	s_cbranch_execz .Lm0b_s2
	global_load_dwordx4 v[136:139], v[176:177], off
	v_add_co_u32_e32 v176, vcc, v180, v176
	s_nop 1
	v_addc_co_u32_e32 v177, vcc, 0, v177, vcc

.LBB0_1877:
	s_mov_b64 s[8:9], 0x70000
	s_andn2_b64 vcc, exec, s[38:39]
	v_lshl_add_u64 v[182:183], v[182:183], 0, s[8:9]
	s_waitcnt lgkmcnt(0)
	s_barrier
	s_cbranch_vccz .LBB0_1744
	s_mov_b32 s20, s13
	s_branch .LBB0_1838
